# attention: counted vmcnt(2) at the per-tile barriers (K pieces issued first, V pieces stay in flight one more tile; exit iteration drains)
# baseline (speedup 1.0000x reference)
; __device__ __forceinline__ void qkt(f32x16& p0, f32x16& p1, const char* Kn, const bf16x8* qr, int r32, int hi) {
;     const char* Kr = Kn + KR_OFF;
;     p0 = f32x16{}; p1 = f32x16{};
;     __builtin_amdgcn_s_setprio(1);
; #pragma unroll
;     for (int d0 = 0; d0 < 8; ++d0) { const int cb = (d0 * 16 + hi * 8) * 2;
;         const bf16x8 b0 = *reinterpret_cast<const bf16x8*>(Kn + KNSWZ(r32, cb));
;         const bf16x8 b1 = *reinterpret_cast<const bf16x8*>(Kn + KNSWZ(32 + r32, cb));
;         p0 = __builtin_amdgcn_mfma_f32_32x32x16_bf16(b0, qr[d0], p0, 0, 0, 0);
;         p1 = __builtin_amdgcn_mfma_f32_32x32x16_bf16(b1, qr[d0], p1, 0, 0, 0); }
; #pragma unroll
;     for (int d0 = 0; d0 < 4; ++d0) { const int cb = (d0 * 16 + hi * 8) * 2;
;         const bf16x8 b0 = *reinterpret_cast<const bf16x8*>(Kr + KRSWZ(r32, cb));
;         const bf16x8 b1 = *reinterpret_cast<const bf16x8*>(Kr + KRSWZ(32 + r32, cb));
;         p0 = __builtin_amdgcn_mfma_f32_32x32x16_bf16(b0, qr[8 + d0], p0, 0, 0, 0);
;         p1 = __builtin_amdgcn_mfma_f32_32x32x16_bf16(b1, qr[8 + d0], p1, 0, 0, 0); }
; }
.LBB0_216:
	s_mul_i32 s0, s9, 0x6000
	s_add_i32 s14, s0, 0
	s_lshl_b32 s13, s9, 14
	s_add_i32 s16, s14, s6
	s_add_i32 s17, s7, s13
	s_add_i32 s18, s14, s8
	s_mov_b32 s13, s10
	s_mov_b32 s10, s15
	s_mul_i32 s0, s13, 0x6000
	s_add_i32 s0, s0, 0
	s_setprio 1
	v_add_u32_e32 v84, s0, v207
	ds_read_b128 v[80:83], v84
	ds_read_b128 v[84:87], v84 offset:8192
	v_add_u32_e32 v168, s0, v210
	ds_read_b128 v[196:199], v168
	ds_read_b128 v[168:171], v168 offset:8192
	v_add_u32_e32 v184, s0, v218
	s_waitcnt lgkmcnt(0)
	v_mfma_f32_32x32x16_bf16 v[96:111], v[80:83], v[156:159], 0
	v_mfma_f32_32x32x16_bf16 v[80:95], v[84:87], v[156:159], 0
	v_mfma_f32_32x32x16_bf16 v[96:111], v[196:199], v[152:155], v[96:111]
	v_mfma_f32_32x32x16_bf16 v[80:95], v[168:171], v[152:155], v[80:95]
	ds_read_b128 v[168:171], v184
	ds_read_b128 v[196:199], v184 offset:8192
	v_add_u32_e32 v184, s0, v221
	s_mov_b32 m0, s16
	s_add_u32 s100, s72, 0x26500000
	s_addc_u32 s101, s73, 0
	global_load_lds_dwordx4 v178, s[100:101]
	s_waitcnt lgkmcnt(0)
	v_mfma_f32_32x32x16_bf16 v[96:111], v[168:171], v[148:151], v[96:111]
	v_mfma_f32_32x32x16_bf16 v[80:95], v[196:199], v[148:151], v[80:95]
	ds_read_b128 v[168:171], v184
	ds_read_b128 v[196:199], v184 offset:8192
	v_add_u32_e32 v184, s0, v222
	s_waitcnt lgkmcnt(0)
	v_mfma_f32_32x32x16_bf16 v[96:111], v[168:171], v[144:147], v[96:111]
	v_mfma_f32_32x32x16_bf16 v[80:95], v[196:199], v[144:147], v[80:95]
	ds_read_b128 v[168:171], v184
	ds_read_b128 v[196:199], v184 offset:8192
	v_add_u32_e32 v184, s0, v223
	s_add_i32 m0, s16, 0x400
	s_nop 0
	global_load_lds_dwordx4 v180, s[100:101]
	s_waitcnt lgkmcnt(0)
	v_mfma_f32_32x32x16_bf16 v[96:111], v[168:171], v[140:143], v[96:111]
	v_mfma_f32_32x32x16_bf16 v[80:95], v[196:199], v[140:143], v[80:95]
	ds_read_b128 v[168:171], v184
	ds_read_b128 v[196:199], v184 offset:8192
	v_add_u32_e32 v184, s0, v224
	v_exp_f32_e32 v233, v73
	s_waitcnt lgkmcnt(0)
	v_mfma_f32_32x32x16_bf16 v[96:111], v[168:171], v[136:139], v[96:111]
	v_mfma_f32_32x32x16_bf16 v[80:95], v[196:199], v[136:139], v[80:95]
	ds_read_b128 v[168:171], v184
	ds_read_b128 v[196:199], v184 offset:8192
	v_add_u32_e32 v184, s0, v225
	s_add_i32 m0, s18, 0x4000
	s_add_u32 s100, s72, 0x21204000
	s_addc_u32 s101, s73, 0
	global_load_lds_dwordx4 v174, s[100:101]
	v_exp_f32_e32 v250, v74
	s_waitcnt lgkmcnt(0)
	v_mfma_f32_32x32x16_bf16 v[96:111], v[168:171], v[132:135], v[96:111]
	v_mfma_f32_32x32x16_bf16 v[80:95], v[196:199], v[132:135], v[80:95]
	ds_read_b128 v[168:171], v184
	ds_read_b128 v[196:199], v184 offset:8192
	v_add_u32_e32 v184, s0, v226
	v_exp_f32_e32 v200, v75
	s_waitcnt lgkmcnt(0)
	v_mfma_f32_32x32x16_bf16 v[96:111], v[168:171], v[128:131], v[96:111]
	v_mfma_f32_32x32x16_bf16 v[80:95], v[196:199], v[128:131], v[80:95]
	ds_read_b128 v[168:171], v184 offset:16384
	ds_read_b128 v[196:199], v184 offset:20480
	v_add_u32_e32 v184, s0, v227
	s_mov_b32 m0, s17
	s_add_u32 s100, s72, 0x26500100
	s_addc_u32 s101, s73, 0
	global_load_lds_dwordx4 v176, s[100:101]
	v_exp_f32_e32 v195, v76
	s_waitcnt lgkmcnt(0)
	v_mfma_f32_32x32x16_bf16 v[96:111], v[168:171], v[124:127], v[96:111]
	v_mfma_f32_32x32x16_bf16 v[80:95], v[196:199], v[124:127], v[80:95]
	ds_read_b128 v[168:171], v184 offset:16384
	ds_read_b128 v[196:199], v184 offset:20480
	v_add_u32_e32 v184, s0, v228
	v_exp_f32_e32 v172, v77
	s_waitcnt lgkmcnt(0)
	v_mfma_f32_32x32x16_bf16 v[96:111], v[168:171], v[120:123], v[96:111]
	v_mfma_f32_32x32x16_bf16 v[80:95], v[196:199], v[120:123], v[80:95]
	ds_read_b128 v[168:171], v184 offset:16384
	ds_read_b128 v[196:199], v184 offset:20480
	v_add_u32_e32 v184, s0, v229
	s_add_i32 m0, s17, 0x400
	s_add_u32 s100, s72, 0x26500180
	s_addc_u32 s101, s73, 0
	global_load_lds_dwordx4 v176, s[100:101]
	v_exp_f32_e32 v173, v78
	s_waitcnt lgkmcnt(0)
	v_mfma_f32_32x32x16_bf16 v[96:111], v[168:171], v[116:119], v[96:111]
	v_mfma_f32_32x32x16_bf16 v[80:95], v[196:199], v[116:119], v[80:95]
	ds_read_b128 v[168:171], v184 offset:16384
	ds_read_b128 v[196:199], v184 offset:20480
	v_exp_f32_e32 v184, v68
	v_exp_f32_e32 v79, v79
	s_waitcnt lgkmcnt(0)
	v_mfma_f32_32x32x16_bf16 v[96:111], v[168:171], v[112:115], v[96:111]
	v_exp_f32_e32 v168, v64
	v_add_f32_e32 v64, 0, v247
	v_add_f32_e32 v64, v249, v64
	v_add_f32_e32 v64, v245, v64
	v_add_f32_e32 v64, v248, v64
	v_add_f32_e32 v64, v244, v64
	v_add_f32_e32 v64, v246, v64
	v_add_f32_e32 v64, v242, v64
	v_add_f32_e32 v64, v243, v64
	v_add_f32_e32 v64, v239, v64
	v_add_f32_e32 v64, v241, v64
	v_add_f32_e32 v64, v238, v64
	v_add_f32_e32 v64, v240, v64
	v_add_f32_e32 v64, v235, v64
	v_exp_f32_e32 v169, v65
	v_add_f32_e32 v64, v237, v64
	v_exp_f32_e32 v170, v66
	v_add_f32_e32 v64, v234, v64
	v_exp_f32_e32 v171, v67
	v_add_f32_e32 v64, v236, v64
	v_add_f32_e32 v64, v168, v64
	v_mfma_f32_32x32x16_bf16 v[80:95], v[196:199], v[112:115], v[80:95]
	v_exp_f32_e32 v196, v69
	v_add_f32_e32 v64, v169, v64
	v_exp_f32_e32 v197, v70
	v_add_f32_e32 v64, v170, v64
	v_exp_f32_e32 v198, v71
	v_add_f32_e32 v64, v171, v64
	v_exp_f32_e32 v199, v72
	v_add_f32_e32 v64, v184, v64
	v_add_f32_e32 v64, v196, v64
	v_add_f32_e32 v64, v197, v64
	v_add_f32_e32 v64, v198, v64
	v_add_f32_e32 v64, v199, v64
	v_add_f32_e32 v64, v233, v64
	v_add_f32_e32 v64, v250, v64
	v_add_f32_e32 v64, v200, v64
	v_add_f32_e32 v64, v195, v64
	v_add_f32_e32 v64, v172, v64
	v_add_f32_e32 v64, v173, v64
	v_add_f32_e32 v231, v79, v64
	v_mov_b32_e32 v232, v231
	v_cvt_pk_bf16_f32 v64, v247, v249
	v_cvt_pk_bf16_f32 v65, v245, v248
	v_cvt_pk_bf16_f32 v66, v244, v246
	s_nop 1
	v_permlane32_swap_b32_e32 v231, v232
	v_cvt_pk_bf16_f32 v67, v242, v243
	v_permlane32_swap_b32_e32 v64, v66
	v_cvt_pk_bf16_f32 v68, v239, v241
	v_cvt_pk_bf16_f32 v69, v238, v240
	v_cvt_pk_bf16_f32 v70, v235, v237
	v_cvt_pk_bf16_f32 v71, v234, v236
	v_cvt_pk_bf16_f32 v72, v168, v169
	v_cvt_pk_bf16_f32 v73, v170, v171
	v_cvt_pk_bf16_f32 v74, v184, v196
	v_cvt_pk_bf16_f32 v75, v197, v198
	v_cvt_pk_bf16_f32 v76, v199, v233
	v_cvt_pk_bf16_f32 v77, v250, v200
	v_cvt_pk_bf16_f32 v78, v195, v172
	v_cvt_pk_bf16_f32 v79, v173, v79
	v_permlane32_swap_b32_e32 v65, v67
	v_permlane32_swap_b32_e32 v68, v70
	v_permlane32_swap_b32_e32 v69, v71
	v_permlane32_swap_b32_e32 v72, v74
	v_permlane32_swap_b32_e32 v73, v75
	v_permlane32_swap_b32_e32 v76, v78
	v_permlane32_swap_b32_e32 v77, v79
	s_setprio 0
	s_lshl_b32 s15, s15, 14
	v_add_u32_e32 v172, s15, v205
	ds_read_b64_tr_b16 v[168:169], v172 offset:0
	ds_read_b64_tr_b16 v[170:171], v172 offset:0x800
	ds_read_b64_tr_b16 v[196:197], v172 offset:0x1000
	ds_read_b64_tr_b16 v[198:199], v172 offset:0x1800
	ds_read_b64_tr_b16 v[234:235], v172 offset:0x2000
	ds_read_b64_tr_b16 v[236:237], v172 offset:0x2800
	ds_read_b64_tr_b16 v[238:239], v172 offset:0x3000
	ds_read_b64_tr_b16 v[240:241], v172 offset:0x3800
	s_waitcnt lgkmcnt(0)
; #define SBAR() __builtin_amdgcn_sched_barrier(0)
; template <bool FIRST>
; __device__ __forceinline__ void partialSM(f32x16& p0, f32x16& p1, float& m_reg, float& mn, float& alpha) {
;     float pmax = p0[0];
; #pragma unroll
;     for (int r = 1; r < 16; ++r) pmax = fmaxf(pmax, p0[r]);
; #pragma unroll
;     for (int r = 0; r < 16; ++r) pmax = fmaxf(pmax, p1[r]);
;     { auto rr = __builtin_amdgcn_permlane32_swap(__float_as_uint(pmax), __float_as_uint(pmax), false, false);
;       pmax = fmaxf(__uint_as_float(rr[0]), __uint_as_float(rr[1])); }
;     if (FIRST) { mn = (fabsf(pmax) <= THRL) ? 0.f : pmax; m_reg = mn; alpha = 1.f; }
;     else if (__builtin_expect(__all(pmax - m_reg <= THRL), 1)) { mn = m_reg; alpha = 1.f; }
;     else { mn = fmaxf(m_reg, pmax); alpha = __builtin_amdgcn_exp2f(m_reg - mn); m_reg = mn; }
;     if (!__builtin_expect(__all(mn == 0.f), 1)) {
; #pragma unroll
;         for (int r = 0; r < 16; ++r) p0[r] = p0[r] - mn;
; #pragma unroll
;         for (int r = 0; r < 16; ++r) p1[r] = p1[r] - mn; }
; #pragma unroll
;     for (int r = 0; r < 16; ++r) p0[r] = __builtin_amdgcn_exp2f(p0[r]);
; template <int D0> __device__ __forceinline__ void pv_one(f32x16& od, int vb, bf16x8 pa0, bf16x8 pa1, bf16x8 pa2, bf16x8 pa3) {
;     const s16x4 l0 = tr_read<v_rd_off(D0, 0, 0)>(vb), h0 = tr_read<v_rd_off(D0, 0, 1)>(vb), l1 = tr_read<v_rd_off(D0, 1, 0)>(vb), h1 = tr_read<v_rd_off(D0, 1, 1)>(vb);
;     const s16x4 l2 = tr_read<v_rd_off(D0, 2, 0)>(vb), h2 = tr_read<v_rd_off(D0, 2, 1)>(vb), l3 = tr_read<v_rd_off(D0, 3, 0)>(vb), h3 = tr_read<v_rd_off(D0, 3, 1)>(vb);
;     asm volatile("s_waitcnt lgkmcnt(0)" ::: "memory"); SBAR();
;     ...
;     od = __builtin_amdgcn_mfma_f32_32x32x16_bf16(pa0, PK(l0, h0), od, 0, 0, 0);
;     od = __builtin_amdgcn_mfma_f32_32x32x16_bf16(pa1, PK(l1, h1), od, 0, 0, 0);
;     od = __builtin_amdgcn_mfma_f32_32x32x16_bf16(pa2, PK(l2, h2), od, 0, 0, 0);
;     od = __builtin_amdgcn_mfma_f32_32x32x16_bf16(pa3, PK(l3, h3), od, 0, 0, 0);
;     ...
; }
; __device__ __forceinline__ void pv_d0(f32x16* o, int vb, bf16x8 pa0, bf16x8 pa1, bf16x8 pa2, bf16x8 pa3) {
;     pv_one<0>(o[0], vb, pa0, pa1, pa2, pa3); pv_one<1>(o[1], vb, pa0, pa1, pa2, pa3); pv_one<2>(o[2], vb, pa0, pa1, pa2, pa3); pv_one<3>(o[3], vb, pa0, pa1, pa2, pa3);
	s_nop 0
	v_mfma_f32_32x32x16_bf16 v[0:15], v[64:67], v[168:171], v[0:15]
	ds_read_b64_tr_b16 v[168:169], v172 offset:0x200
	ds_read_b64_tr_b16 v[170:171], v172 offset:0xa00
	v_mfma_f32_32x32x16_bf16 v[0:15], v[68:71], v[196:199], v[0:15]
	ds_read_b64_tr_b16 v[196:197], v172 offset:0x1200
	ds_read_b64_tr_b16 v[198:199], v172 offset:0x1a00
	v_mfma_f32_32x32x16_bf16 v[0:15], v[72:75], v[234:237], v[0:15]
	ds_read_b64_tr_b16 v[234:235], v172 offset:0x2200
	ds_read_b64_tr_b16 v[236:237], v172 offset:0x2a00
	v_mfma_f32_32x32x16_bf16 v[0:15], v[76:79], v[238:241], v[0:15]
	ds_read_b64_tr_b16 v[238:239], v172 offset:0x3200
	ds_read_b64_tr_b16 v[240:241], v172 offset:0x3a00
	s_waitcnt lgkmcnt(0)
	v_mfma_f32_32x32x16_bf16 v[48:63], v[64:67], v[168:171], v[48:63]
	ds_read_b64_tr_b16 v[168:169], v172 offset:0x400
	ds_read_b64_tr_b16 v[170:171], v172 offset:0xc00
	v_mfma_f32_32x32x16_bf16 v[48:63], v[68:71], v[196:199], v[48:63]
	ds_read_b64_tr_b16 v[196:197], v172 offset:0x1400
	ds_read_b64_tr_b16 v[198:199], v172 offset:0x1c00
	v_mfma_f32_32x32x16_bf16 v[48:63], v[72:75], v[234:237], v[48:63]
	ds_read_b64_tr_b16 v[234:235], v172 offset:0x2400
	ds_read_b64_tr_b16 v[236:237], v172 offset:0x2c00
	v_mfma_f32_32x32x16_bf16 v[48:63], v[76:79], v[238:241], v[48:63]
	ds_read_b64_tr_b16 v[238:239], v172 offset:0x3400
	ds_read_b64_tr_b16 v[240:241], v172 offset:0x3c00
	s_waitcnt lgkmcnt(0)
	v_mfma_f32_32x32x16_bf16 v[32:47], v[64:67], v[168:171], v[32:47]
	ds_read_b64_tr_b16 v[168:169], v172 offset:0x600
	ds_read_b64_tr_b16 v[170:171], v172 offset:0xe00
	v_mfma_f32_32x32x16_bf16 v[32:47], v[68:71], v[196:199], v[32:47]
	ds_read_b64_tr_b16 v[196:197], v172 offset:0x1600
	ds_read_b64_tr_b16 v[198:199], v172 offset:0x1e00
	v_mfma_f32_32x32x16_bf16 v[32:47], v[72:75], v[234:237], v[32:47]
	ds_read_b64_tr_b16 v[234:235], v172 offset:0x2600
	ds_read_b64_tr_b16 v[236:237], v172 offset:0x2e00
	v_mfma_f32_32x32x16_bf16 v[32:47], v[76:79], v[238:241], v[32:47]
	ds_read_b64_tr_b16 v[238:239], v172 offset:0x3600
	ds_read_b64_tr_b16 v[240:241], v172 offset:0x3e00
	s_waitcnt lgkmcnt(0)
	v_mfma_f32_32x32x16_bf16 v[16:31], v[64:67], v[168:171], v[16:31]
	v_max_f32_e32 v64, v97, v97
	v_max_f32_e32 v65, v96, v96
	v_max_f32_e32 v64, v65, v64
	v_max3_f32 v64, v64, v98, v99
	v_max3_f32 v64, v64, v100, v101
	v_max3_f32 v64, v64, v102, v103
	v_max3_f32 v64, v64, v104, v105
	v_mfma_f32_32x32x16_bf16 v[16:31], v[68:71], v[196:199], v[16:31]
	v_max3_f32 v64, v64, v106, v107
	v_max3_f32 v64, v64, v108, v109
	v_max3_f32 v64, v64, v110, v111
	v_max3_f32 v64, v64, v80, v81
	v_max3_f32 v64, v64, v82, v83
	v_max3_f32 v64, v64, v84, v85
	v_max3_f32 v64, v64, v86, v87
	v_mfma_f32_32x32x16_bf16 v[16:31], v[72:75], v[234:237], v[16:31]
	v_max3_f32 v64, v64, v88, v89
	v_max3_f32 v64, v64, v90, v91
	v_max3_f32 v64, v64, v92, v93
	v_max3_f32 v64, v64, v94, v95
	v_mov_b32_e32 v65, v64
	s_nop 1
	v_permlane32_swap_b32_e32 v64, v65
	v_max_f32_e32 v65, v65, v65
	v_max_f32_e32 v64, v64, v64
	v_mfma_f32_32x32x16_bf16 v[16:31], v[76:79], v[238:241], v[16:31]
	v_max_f32_e32 v64, v64, v65
	v_sub_f32_e32 v65, v64, v182
	s_mov_b32 s0, 0x41300000
	v_cmp_ge_f32_e32 vcc, s0, v65
	v_mov_b32_e32 v184, v182
	v_mov_b32_e32 v233, 1.0
	s_cmp_eq_u64 vcc, exec
	s_cbranch_scc0 .Latt_slow1
	s_cmp_lg_u32 s19, 0
	s_cbranch_scc0 .LBB0_228
.LBB0_221:
	v_exp_f32_e32 v182, v98
	v_exp_f32_e32 v172, v96
	v_exp_f32_e32 v173, v97
	v_exp_f32_e32 v195, v99
	v_exp_f32_e32 v196, v100
	v_exp_f32_e32 v197, v101
	v_exp_f32_e32 v198, v102
	v_exp_f32_e32 v199, v103
	v_exp_f32_e32 v200, v104
	v_exp_f32_e32 v234, v105
	v_exp_f32_e32 v235, v106
	v_exp_f32_e32 v236, v107
	v_exp_f32_e32 v237, v108
	v_exp_f32_e32 v238, v109
	v_exp_f32_e32 v239, v110
	v_exp_f32_e32 v240, v111
	s_mul_i32 s0, s10, 0x6000
	s_add_i32 s16, s0, 0
	s_add_i32 s17, s16, s6
	s_add_i32 s18, s16, s8
	s_waitcnt vmcnt(2) lgkmcnt(0)
	s_barrier
	s_add_i32 s15, s7, s15
	s_setprio 1
	v_add_u32_e32 v68, s14, v207
	ds_read_b128 v[64:67], v68
	ds_read_b128 v[68:71], v68 offset:8192
	v_add_u32_e32 v186, s14, v210
	ds_read_b128 v[168:171], v186
	ds_read_b128 v[186:189], v186 offset:8192
	s_waitcnt lgkmcnt(0)
	v_mfma_f32_32x32x16_bf16 v[96:111], v[64:67], v[156:159], 0
	v_mfma_f32_32x32x16_bf16 v[64:79], v[68:71], v[156:159], 0
	v_mfma_f32_32x32x16_bf16 v[96:111], v[168:171], v[152:155], v[96:111]
	v_mfma_f32_32x32x16_bf16 v[64:79], v[186:189], v[152:155], v[64:79]
	v_add_u32_e32 v186, s14, v218
	ds_read_b128 v[168:171], v186
	ds_read_b128 v[186:189], v186 offset:8192
	s_mov_b32 m0, s17
	s_add_u32 s100, s72, 0x26580000
	s_addc_u32 s101, s73, 0
	global_load_lds_dwordx4 v178, s[100:101]
	s_waitcnt lgkmcnt(0)
	v_mfma_f32_32x32x16_bf16 v[96:111], v[168:171], v[148:151], v[96:111]
	v_mfma_f32_32x32x16_bf16 v[64:79], v[186:189], v[148:151], v[64:79]
	v_add_u32_e32 v186, s14, v221
	ds_read_b128 v[168:171], v186
	ds_read_b128 v[186:189], v186 offset:8192
	s_waitcnt lgkmcnt(0)
	v_mfma_f32_32x32x16_bf16 v[96:111], v[168:171], v[144:147], v[96:111]
	v_mfma_f32_32x32x16_bf16 v[64:79], v[186:189], v[144:147], v[64:79]
	v_add_u32_e32 v186, s14, v222
	ds_read_b128 v[168:171], v186
	ds_read_b128 v[186:189], v186 offset:8192
	s_add_i32 m0, s17, 0x400
	s_nop 0
	global_load_lds_dwordx4 v180, s[100:101]
	v_exp_f32_e32 v190, v88
	s_waitcnt lgkmcnt(0)
	v_mfma_f32_32x32x16_bf16 v[96:111], v[168:171], v[140:143], v[96:111]
	v_mfma_f32_32x32x16_bf16 v[64:79], v[186:189], v[140:143], v[64:79]
	v_add_u32_e32 v186, s14, v223
	ds_read_b128 v[168:171], v186
	ds_read_b128 v[186:189], v186 offset:8192
	v_exp_f32_e32 v191, v89
	s_waitcnt lgkmcnt(0)
; __device__ __forceinline__ void qkt(f32x16& p0, f32x16& p1, const char* Kn, const bf16x8* qr, int r32, int hi) {
;     const char* Kr = Kn + KR_OFF;
;     p0 = f32x16{}; p1 = f32x16{};
;     __builtin_amdgcn_s_setprio(1);
; #pragma unroll
;     for (int d0 = 0; d0 < 8; ++d0) { const int cb = (d0 * 16 + hi * 8) * 2;
;         const bf16x8 b0 = *reinterpret_cast<const bf16x8*>(Kn + KNSWZ(r32, cb));
;         const bf16x8 b1 = *reinterpret_cast<const bf16x8*>(Kn + KNSWZ(32 + r32, cb));
;         p0 = __builtin_amdgcn_mfma_f32_32x32x16_bf16(b0, qr[d0], p0, 0, 0, 0);
;         p1 = __builtin_amdgcn_mfma_f32_32x32x16_bf16(b1, qr[d0], p1, 0, 0, 0); }
; #pragma unroll
;     for (int d0 = 0; d0 < 4; ++d0) { const int cb = (d0 * 16 + hi * 8) * 2;
;         const bf16x8 b0 = *reinterpret_cast<const bf16x8*>(Kr + KRSWZ(r32, cb));
;         const bf16x8 b1 = *reinterpret_cast<const bf16x8*>(Kr + KRSWZ(32 + r32, cb));
;         p0 = __builtin_amdgcn_mfma_f32_32x32x16_bf16(b0, qr[8 + d0], p0, 0, 0, 0);
;         p1 = __builtin_amdgcn_mfma_f32_32x32x16_bf16(b1, qr[8 + d0], p1, 0, 0, 0); }
; }
	v_mfma_f32_32x32x16_bf16 v[96:111], v[168:171], v[136:139], v[96:111]
	v_mfma_f32_32x32x16_bf16 v[64:79], v[186:189], v[136:139], v[64:79]
	v_add_u32_e32 v186, s14, v224
	ds_read_b128 v[168:171], v186
	ds_read_b128 v[186:189], v186 offset:8192
	s_add_i32 m0, s18, 0x4000
	s_add_u32 s100, s72, 0x21206000
	s_addc_u32 s101, s73, 0
	global_load_lds_dwordx4 v174, s[100:101]
	v_exp_f32_e32 v192, v90
	s_waitcnt lgkmcnt(0)
	v_mfma_f32_32x32x16_bf16 v[96:111], v[168:171], v[132:135], v[96:111]
	v_mfma_f32_32x32x16_bf16 v[64:79], v[186:189], v[132:135], v[64:79]
	v_add_u32_e32 v186, s14, v225
	ds_read_b128 v[168:171], v186
	ds_read_b128 v[186:189], v186 offset:8192
	v_exp_f32_e32 v193, v91
	s_waitcnt lgkmcnt(0)
	v_mfma_f32_32x32x16_bf16 v[96:111], v[168:171], v[128:131], v[96:111]
	v_mfma_f32_32x32x16_bf16 v[64:79], v[186:189], v[128:131], v[64:79]
	v_add_u32_e32 v186, s14, v226
	ds_read_b128 v[168:171], v186 offset:16384
	ds_read_b128 v[186:189], v186 offset:20480
	s_mov_b32 m0, s15
	s_add_u32 s100, s72, 0x26580100
	s_addc_u32 s101, s73, 0
	global_load_lds_dwordx4 v176, s[100:101]
	v_exp_f32_e32 v241, v92
	s_waitcnt lgkmcnt(0)
	v_mfma_f32_32x32x16_bf16 v[96:111], v[168:171], v[124:127], v[96:111]
	v_mfma_f32_32x32x16_bf16 v[64:79], v[186:189], v[124:127], v[64:79]
	v_add_u32_e32 v186, s14, v227
	ds_read_b128 v[168:171], v186 offset:16384
	ds_read_b128 v[186:189], v186 offset:20480
	v_exp_f32_e32 v242, v93
	s_waitcnt lgkmcnt(0)
	v_mfma_f32_32x32x16_bf16 v[96:111], v[168:171], v[120:123], v[96:111]
	v_mfma_f32_32x32x16_bf16 v[64:79], v[186:189], v[120:123], v[64:79]
	v_add_u32_e32 v186, s14, v228
	ds_read_b128 v[168:171], v186 offset:16384
	ds_read_b128 v[186:189], v186 offset:20480
	s_add_i32 m0, s15, 0x400
	s_add_u32 s100, s72, 0x26580180
	s_addc_u32 s101, s73, 0
	global_load_lds_dwordx4 v176, s[100:101]
	v_exp_f32_e32 v94, v94
	s_waitcnt lgkmcnt(0)
	v_mfma_f32_32x32x16_bf16 v[96:111], v[168:171], v[116:119], v[96:111]
	v_mfma_f32_32x32x16_bf16 v[64:79], v[186:189], v[116:119], v[64:79]
	v_add_u32_e32 v186, s14, v229
	ds_read_b128 v[168:171], v186 offset:16384
	ds_read_b128 v[186:189], v186 offset:20480
	v_exp_f32_e32 v95, v95
	s_waitcnt lgkmcnt(0)
	v_mfma_f32_32x32x16_bf16 v[96:111], v[168:171], v[112:115], v[96:111]
	v_exp_f32_e32 v168, v80
	v_add_f32_e32 v80, 0, v172
	v_add_f32_e32 v80, v173, v80
	v_add_f32_e32 v80, v182, v80
	v_add_f32_e32 v80, v195, v80
	v_add_f32_e32 v80, v196, v80
	v_add_f32_e32 v80, v197, v80
	v_add_f32_e32 v80, v198, v80
	v_add_f32_e32 v80, v199, v80
	v_add_f32_e32 v80, v200, v80
	v_add_f32_e32 v80, v234, v80
	v_add_f32_e32 v80, v235, v80
	v_add_f32_e32 v80, v236, v80
	v_add_f32_e32 v80, v237, v80
	v_exp_f32_e32 v169, v81
	v_add_f32_e32 v80, v238, v80
	v_exp_f32_e32 v170, v82
	v_add_f32_e32 v80, v239, v80
	v_exp_f32_e32 v171, v83
	v_add_f32_e32 v80, v240, v80
	v_mfma_f32_32x32x16_bf16 v[64:79], v[186:189], v[112:115], v[64:79]
	v_exp_f32_e32 v186, v84
	v_add_f32_e32 v80, v168, v80
	v_exp_f32_e32 v187, v85
	v_add_f32_e32 v80, v169, v80
	v_exp_f32_e32 v188, v86
	v_add_f32_e32 v80, v170, v80
	v_exp_f32_e32 v189, v87
	v_add_f32_e32 v80, v171, v80
	v_add_f32_e32 v80, v186, v80
	v_add_f32_e32 v80, v187, v80
	v_add_f32_e32 v80, v188, v80
	v_add_f32_e32 v80, v189, v80
	v_add_f32_e32 v80, v190, v80
	v_add_f32_e32 v80, v191, v80
	v_add_f32_e32 v80, v192, v80
	v_add_f32_e32 v80, v193, v80
	v_add_f32_e32 v80, v241, v80
	v_add_f32_e32 v80, v242, v80
	v_add_f32_e32 v80, v94, v80
	v_add_f32_e32 v80, v95, v80
	v_mov_b32_e32 v81, v80
	v_cvt_pk_bf16_f32 v82, v172, v173
	v_cvt_pk_bf16_f32 v83, v182, v195
	v_cvt_pk_bf16_f32 v84, v196, v197
	s_nop 1
	v_permlane32_swap_b32_e32 v80, v81
	v_cvt_pk_bf16_f32 v85, v198, v199
	v_permlane32_swap_b32_e32 v82, v84
	v_cvt_pk_bf16_f32 v86, v200, v234
	v_cvt_pk_bf16_f32 v87, v235, v236
	v_cvt_pk_bf16_f32 v88, v237, v238
	v_cvt_pk_bf16_f32 v89, v239, v240
	v_cvt_pk_bf16_f32 v90, v168, v169
	v_cvt_pk_bf16_f32 v91, v170, v171
	v_cvt_pk_bf16_f32 v92, v186, v187
	v_cvt_pk_bf16_f32 v93, v188, v189
	v_cvt_pk_bf16_f32 v168, v190, v191
	v_cvt_pk_bf16_f32 v169, v192, v193
	v_cvt_pk_bf16_f32 v170, v241, v242
	v_cvt_pk_bf16_f32 v171, v94, v95
	v_permlane32_swap_b32_e32 v83, v85
	v_permlane32_swap_b32_e32 v86, v88
	v_permlane32_swap_b32_e32 v87, v89
	v_permlane32_swap_b32_e32 v90, v92
	v_permlane32_swap_b32_e32 v91, v93
	v_permlane32_swap_b32_e32 v168, v170
	v_permlane32_swap_b32_e32 v169, v171
	s_setprio 0
	v_lshl_add_u32 v94, s13, 14, v205
	ds_read_b64_tr_b16 v[186:187], v94 offset:0
	ds_read_b64_tr_b16 v[188:189], v94 offset:0x800
	ds_read_b64_tr_b16 v[190:191], v94 offset:0x1000
	ds_read_b64_tr_b16 v[192:193], v94 offset:0x1800
	ds_read_b64_tr_b16 v[196:197], v94 offset:0x2000
	ds_read_b64_tr_b16 v[198:199], v94 offset:0x2800
	ds_read_b64_tr_b16 v[234:235], v94 offset:0x3000
	ds_read_b64_tr_b16 v[236:237], v94 offset:0x3800
	s_waitcnt lgkmcnt(0)
; #define SBAR() __builtin_amdgcn_sched_barrier(0)
; #define WAIT_BAR() asm volatile("s_waitcnt vmcnt(0) lgkmcnt(0)\n\ts_barrier" ::: "memory")
; #define RESC(a) do { if (__any((a) < 1.f)) { if (hi == 0) al_l[r32] = (a); asm volatile("s_waitcnt lgkmcnt(0)" ::: "memory"); \
;     _Pragma("unroll") for (int d = 0; d < 4; ++d) _Pragma("unroll") for (int r = 0; r < 16; ++r) o[d][r] *= al_l[crow(r, hi)]; } } while (0)
; #define ROT() do { const int t_ = s_prev; s_prev = s_cur; s_cur = s_next; s_next = t_; } while (0)
; __device__ __forceinline__ void attn_unit(const bf16_t* __restrict__ Qb, const bf16_t* __restrict__ Kn, const bf16_t* __restrict__ Vh, const bf16_t* __restrict__ Kr,
;                                           bf16_t* __restrict__ Ob, int seq, char* lds, int wv_) { LAUNDER_IDS;
;     ...
;         RESC(alA); WAIT_BAR(); ROT();
;     }
;     SBAR(); qkt(pB0, pB1, lds + OFF_K + s_cur * SLOT_K, qr, r32, hi);
	s_nop 0
	v_mfma_f32_32x32x16_bf16 v[0:15], v[82:85], v[186:189], v[0:15]
	ds_read_b64_tr_b16 v[186:187], v94 offset:0x200
	ds_read_b64_tr_b16 v[188:189], v94 offset:0xa00
	v_mfma_f32_32x32x16_bf16 v[0:15], v[86:89], v[190:193], v[0:15]
	ds_read_b64_tr_b16 v[190:191], v94 offset:0x1200
	ds_read_b64_tr_b16 v[192:193], v94 offset:0x1a00
	v_mfma_f32_32x32x16_bf16 v[0:15], v[90:93], v[196:199], v[0:15]
	ds_read_b64_tr_b16 v[196:197], v94 offset:0x2200
	ds_read_b64_tr_b16 v[198:199], v94 offset:0x2a00
	v_mfma_f32_32x32x16_bf16 v[0:15], v[168:171], v[234:237], v[0:15]
	ds_read_b64_tr_b16 v[234:235], v94 offset:0x3200
	ds_read_b64_tr_b16 v[236:237], v94 offset:0x3a00
	s_waitcnt lgkmcnt(0)
	v_mfma_f32_32x32x16_bf16 v[48:63], v[82:85], v[186:189], v[48:63]
	ds_read_b64_tr_b16 v[186:187], v94 offset:0x400
	ds_read_b64_tr_b16 v[188:189], v94 offset:0xc00
	v_mfma_f32_32x32x16_bf16 v[48:63], v[86:89], v[190:193], v[48:63]
	ds_read_b64_tr_b16 v[190:191], v94 offset:0x1400
	ds_read_b64_tr_b16 v[192:193], v94 offset:0x1c00
	v_mfma_f32_32x32x16_bf16 v[48:63], v[90:93], v[196:199], v[48:63]
	ds_read_b64_tr_b16 v[196:197], v94 offset:0x2400
	ds_read_b64_tr_b16 v[198:199], v94 offset:0x2c00
	v_mfma_f32_32x32x16_bf16 v[48:63], v[168:171], v[234:237], v[48:63]
	ds_read_b64_tr_b16 v[234:235], v94 offset:0x3400
	ds_read_b64_tr_b16 v[236:237], v94 offset:0x3c00
	s_waitcnt lgkmcnt(0)
	v_mfma_f32_32x32x16_bf16 v[32:47], v[82:85], v[186:189], v[32:47]
	ds_read_b64_tr_b16 v[186:187], v94 offset:0x600
	ds_read_b64_tr_b16 v[188:189], v94 offset:0xe00
	v_mfma_f32_32x32x16_bf16 v[32:47], v[86:89], v[190:193], v[32:47]
	ds_read_b64_tr_b16 v[190:191], v94 offset:0x1600
	ds_read_b64_tr_b16 v[192:193], v94 offset:0x1e00
	v_mfma_f32_32x32x16_bf16 v[32:47], v[90:93], v[196:199], v[32:47]
	ds_read_b64_tr_b16 v[196:197], v94 offset:0x2600
	ds_read_b64_tr_b16 v[198:199], v94 offset:0x2e00
	v_mfma_f32_32x32x16_bf16 v[32:47], v[168:171], v[234:237], v[32:47]
	ds_read_b64_tr_b16 v[234:235], v94 offset:0x3600
	ds_read_b64_tr_b16 v[236:237], v94 offset:0x3e00
	s_waitcnt lgkmcnt(0)
	v_mfma_f32_32x32x16_bf16 v[16:31], v[82:85], v[186:189], v[16:31]
	v_max_f32_e32 v82, v97, v97
	v_max_f32_e32 v83, v96, v96
	v_max_f32_e32 v82, v83, v82
	v_max3_f32 v82, v82, v98, v99
	v_max3_f32 v82, v82, v100, v101
	v_max3_f32 v82, v82, v102, v103
	v_max3_f32 v82, v82, v104, v105
	v_mfma_f32_32x32x16_bf16 v[16:31], v[86:89], v[190:193], v[16:31]
	v_max3_f32 v82, v82, v106, v107
	v_max3_f32 v82, v82, v108, v109
	v_max3_f32 v82, v82, v110, v111
	v_max3_f32 v82, v82, v64, v65
	v_max3_f32 v82, v82, v66, v67
	v_max3_f32 v82, v82, v68, v69
	v_max3_f32 v82, v82, v70, v71
	v_mfma_f32_32x32x16_bf16 v[16:31], v[90:93], v[196:199], v[16:31]
	v_max3_f32 v82, v82, v72, v73
	v_max3_f32 v82, v82, v74, v75
	v_max3_f32 v82, v82, v76, v77
	v_max3_f32 v82, v82, v78, v79
	v_mov_b32_e32 v83, v82
	s_nop 1
	v_permlane32_swap_b32_e32 v82, v83
	v_max_f32_e32 v83, v83, v83
	v_max_f32_e32 v82, v82, v82
	v_mfma_f32_32x32x16_bf16 v[16:31], v[168:171], v[234:237], v[16:31]
	v_max_f32_e32 v82, v82, v83
	v_sub_f32_e32 v83, v82, v184
	s_mov_b32 s0, 0x41300000
	v_cmp_ge_f32_e32 vcc, s0, v83
	v_mov_b32_e32 v182, v184
	s_cmp_eq_u64 vcc, exec
	s_cbranch_scc0 .Latt_slow2
	s_cmp_lg_u32 s19, 0
	s_cbranch_scc0 .LBB0_229
	v_mov_b32_e32 v184, 1.0
.LBB0_226:
	v_exp_f32_e32 v247, v96
	v_exp_f32_e32 v249, v97
	v_exp_f32_e32 v245, v98
	v_exp_f32_e32 v248, v99
	v_exp_f32_e32 v244, v100
	v_exp_f32_e32 v246, v101
	v_exp_f32_e32 v242, v102
	v_exp_f32_e32 v243, v103
	v_exp_f32_e32 v239, v104
	v_exp_f32_e32 v241, v105
	v_exp_f32_e32 v238, v106
	v_exp_f32_e32 v240, v107
	v_exp_f32_e32 v235, v108
	v_exp_f32_e32 v237, v109
	v_exp_f32_e32 v234, v110
	v_exp_f32_e32 v236, v111
	v_add_f32_e32 v82, v231, v232
	s_mov_b64 s[0:1], 0x4000
	v_fmac_f32_e32 v82, v230, v203
	v_add_f32_e32 v203, v80, v81
	s_add_i32 s11, s11, 2
	v_lshl_add_u64 v[174:175], v[174:175], 0, s[0:1]
	s_mov_b64 s[0:1], 0x100000
	v_fmac_f32_e32 v203, v82, v233
	v_lshl_add_u64 v[176:177], v[176:177], 0, s[0:1]
	v_lshl_add_u64 v[178:179], v[178:179], 0, s[0:1]
	v_lshl_add_u64 v[180:181], v[180:181], 0, s[0:1]
	v_mov_b32_e32 v230, v184
	s_cmpk_gt_u32 s11, 0x7c
	s_cbranch_scc0 .Latt_w2
	s_waitcnt vmcnt(0)
.Latt_w2:
	s_waitcnt vmcnt(2) lgkmcnt(0)
	s_barrier
	s_cbranch_scc1 .LBB0_230
	s_mov_b32 s15, s9
	s_mov_b32 s9, s13
	s_branch .LBB0_216
